# grid barrier: non-leader workgroups poll the top-level generation word directly instead of the per-XCD one (one hop less)
# baseline (speedup 1.0000x reference)
; DI unsigned xb_ld(unsigned* p)              { return __hip_atomic_load(p, __ATOMIC_RELAXED, __HIP_MEMORY_SCOPE_AGENT); }
; DI unsigned xb_add(unsigned* p, unsigned v) { return __hip_atomic_fetch_add(p, v, __ATOMIC_RELAXED, __HIP_MEMORY_SCOPE_AGENT); }
; #define XB_SPIN(cond, bar) do { unsigned _sp = 0; while (cond) { __builtin_amdgcn_s_sleep(1); \
;     if ((++_sp & 255u) == 0u) { if (xb_ld(&(bar)[XB_TMO])) break; if (_sp > XB_SPIN_CAP) { atomicAdd(&(bar)[XB_TMO], 1u); break; } } } } while (0)
; DI void xcd_barrier(const XcdBarrier& b) {
;     ...
;         const unsigned old = xb_add(&bar[XB_XSUB(b.x)], 1u);
;         const unsigned gen = old / nloc;
;         if (old + 1u == (gen + 1u) * nloc) {
;             __builtin_amdgcn_fence(__ATOMIC_RELEASE, "agent");
;             asm volatile("s_waitcnt vmcnt(0)" ::: "memory");
;             const unsigned og = xb_add(&bar[XB_TOP], 1u);
;             const unsigned tg = og / nx;
;             if (og + 1u == (tg + 1u) * nx) xb_add(&bar[XB_TOPGEN], 1u);
;             else XB_SPIN(xb_ld(&bar[XB_TOPGEN]) == tg, bar);
;             __builtin_amdgcn_fence(__ATOMIC_ACQUIRE, "agent");
;             xb_add(&bar[XB_XGEN(b.x)], 1u);
;             asm volatile("s_waitcnt vmcnt(0)" ::: "memory");
;         } else {
;             XB_SPIN(xb_ld(&bar[XB_XGEN(b.x)]) == gen, bar);
.LBB0_371:
	s_or_b64 exec, exec, s[6:7]
	v_cvt_f32_u32_e32 v4, v2
	s_waitcnt vmcnt(0)
	v_readfirstlane_b32 s6, v3
	v_sub_u32_e32 v3, 0, v2
	v_rcp_iflag_f32_e32 v4, v4
	v_add_u32_e32 v5, s6, v1
	v_mul_f32_e32 v4, 0x4f7ffffe, v4
	v_cvt_u32_f32_e32 v4, v4
	v_mul_lo_u32 v1, v3, v4
	v_mul_hi_u32 v1, v4, v1
	v_add_u32_e32 v1, v4, v1
	v_mul_hi_u32 v1, v5, v1
	v_mul_lo_u32 v3, v1, v2
	v_sub_u32_e32 v3, v5, v3
	v_add_u32_e32 v4, 1, v1
	v_cmp_ge_u32_e32 vcc, v3, v2
	s_nop 1
	v_cndmask_b32_e32 v1, v1, v4, vcc
	v_sub_u32_e32 v4, v3, v2
	v_cndmask_b32_e32 v3, v3, v4, vcc
	v_add_u32_e32 v4, 1, v1
	v_cmp_ge_u32_e32 vcc, v3, v2
	v_add_u32_e32 v3, 1, v5
	s_nop 0
	v_cndmask_b32_e32 v1, v1, v4, vcc
	v_mul_lo_u32 v4, v2, v1
	v_add_u32_e32 v2, v4, v2
	v_cmp_ne_u32_e32 vcc, v3, v2
	s_and_saveexec_b64 s[6:7], vcc
	s_xor_b64 s[6:7], exec, s[6:7]
	s_cbranch_execz .LBB0_385
	v_readlane_b32 s8, v255, 15
	v_readlane_b32 s9, v255, 16
	s_waitcnt lgkmcnt(0)
	s_nop 3
	global_load_dword v0, v193, s[8:9] sc1
	s_waitcnt vmcnt(0)
	v_cmp_eq_u32_e32 vcc, v0, v1
	s_and_saveexec_b64 s[8:9], vcc
	s_cbranch_execz .LBB0_384
	s_mov_b32 s46, 1
	s_mov_b64 s[28:29], 0
	s_branch .LBB0_375

; DI unsigned xb_ld(unsigned* p)              { return __hip_atomic_load(p, __ATOMIC_RELAXED, __HIP_MEMORY_SCOPE_AGENT); }
; #define XB_SPIN(cond, bar) do { unsigned _sp = 0; while (cond) { __builtin_amdgcn_s_sleep(1); \
;     if ((++_sp & 255u) == 0u) { if (xb_ld(&(bar)[XB_TMO])) break; if (_sp > XB_SPIN_CAP) { atomicAdd(&(bar)[XB_TMO], 1u); break; } } } } while (0)
; DI void xcd_barrier(const XcdBarrier& b) {
;     ...
;             XB_SPIN(xb_ld(&bar[XB_XGEN(b.x)]) == gen, bar);
.LBB0_377:
	v_readlane_b32 s40, v255, 15
	v_readlane_b32 s41, v255, 16
	s_add_i32 s46, s46, 1
	s_mov_b64 s[42:43], -1
	s_nop 2
	global_load_dword v0, v193, s[40:41] sc1
	s_waitcnt vmcnt(0)
	v_cmp_ne_u32_e32 vcc, v0, v1
	s_orn2_b64 s[40:41], vcc, exec
	s_branch .LBB0_374
